# select pass 0: per-lane 64-bin histogram scan rewritten as 16 conflict-free ds_read_b128 in two batches + v_bfe_u32 (was 64 ds_read_b32 waited in pairs)
# speedup vs baseline: 1.0129x; 1.0077x over previous
; template <int PASS>
; DI void sel_pass(SelSmem* S, const uint32_t (&sk)[32][2], int ntiles, uint32_t (&pf)[2]) {
;     ...
;   {
;     constexpr int PER = (PASS == 0 || PASS == 3) ? 64 : 16;
;     const int pair = wave >> 1, sh = (wave & 1) * 16;
;     const uint32_t need = S->need[wave];
;     const uint32_t prevp = S->pfx[wave];
;     const uint32_t* hp = &S->hist[pair][lane * PER];
;     uint32_t tot = 0;
;     for (int c = 0; c < PER; ++c) tot += (hp[(c + lane) & (PER - 1)] >> sh) & 0xffffu;
;     uint32_t incl = tot;
; #pragma unroll
;     for (int off = 1; off < 64; off <<= 1) {
;       uint32_t v = __shfl_down(incl, off);
;       if (lane + off < 64) incl += v;
;     }
;     const uint32_t sfx = incl - tot;
;     const bool cross = (sfx < need) && (need <= sfx + tot);
.LBB0_587:
	s_lshl_b32 s0, s44, 7
	v_and_b32_e32 v5, 63, v1
	s_and_b32 s18, s0, 0xffffc000
	v_add_u32_e32 v9, 1, v1
	s_lshl_b32 s16, s15, 4
	s_lshl_b32 s15, s15, 2
	v_lshl_or_b32 v7, v5, 8, s18
	v_and_b32_e32 v9, 63, v9
	v_mov_b32_e32 v4, s15
	v_lshl_or_b32 v8, v5, 2, v7
	v_lshl_or_b32 v9, v9, 2, v7
	s_waitcnt lgkmcnt(0)
	s_barrier
	ds_read_b32 v4, v4 offset:32784
	v_and_b32_e32 v9, 15, v5
	v_mov_b32_e32 v8, 0
	v_lshl_or_b32 v10, v9, 4, v7
	ds_read_b128 v[96:99], v10
	v_add_u32_e32 v10, 1, v9
	v_and_b32_e32 v10, 15, v10
	v_lshl_or_b32 v10, v10, 4, v7
	ds_read_b128 v[100:103], v10
	v_add_u32_e32 v10, 2, v9
	v_and_b32_e32 v10, 15, v10
	v_lshl_or_b32 v10, v10, 4, v7
	ds_read_b128 v[104:107], v10
	v_add_u32_e32 v10, 3, v9
	v_and_b32_e32 v10, 15, v10
	v_lshl_or_b32 v10, v10, 4, v7
	ds_read_b128 v[130:133], v10
	v_add_u32_e32 v10, 4, v9
	v_and_b32_e32 v10, 15, v10
	v_lshl_or_b32 v10, v10, 4, v7
	ds_read_b128 v[190:193], v10
	v_add_u32_e32 v10, 5, v9
	v_and_b32_e32 v10, 15, v10
	v_lshl_or_b32 v10, v10, 4, v7
	ds_read_b128 v[194:197], v10
	v_add_u32_e32 v10, 6, v9
	v_and_b32_e32 v10, 15, v10
	v_lshl_or_b32 v10, v10, 4, v7
	ds_read_b128 v[198:201], v10
	v_add_u32_e32 v10, 7, v9
	v_and_b32_e32 v10, 15, v10
	v_lshl_or_b32 v10, v10, 4, v7
	ds_read_b128 v[230:233], v10
	v_and_b32_e32 v11, 63, v213
	v_cmp_ne_u32_e32 vcc, 63, v11
	v_cmp_eq_u32_e64 s[0:1], 63, v5
	v_cmp_gt_u32_e64 s[44:45], 62, v5
	v_cmp_gt_u32_e64 s[46:47], 60, v5
	v_cmp_gt_u32_e64 s[48:49], 56, v5
	v_cmp_gt_u32_e64 s[50:51], 48, v5
	v_cmp_gt_u32_e64 s[52:53], 32, v5
	s_mov_b32 s55, s57
	s_waitcnt lgkmcnt(0)
	v_bfe_u32 v96, v96, s16, 16
	v_bfe_u32 v97, v97, s16, 16
	v_bfe_u32 v98, v98, s16, 16
	v_bfe_u32 v99, v99, s16, 16
	v_add3_u32 v8, v8, v96, v97
	v_add3_u32 v8, v8, v98, v99
	v_bfe_u32 v100, v100, s16, 16
	v_bfe_u32 v101, v101, s16, 16
	v_bfe_u32 v102, v102, s16, 16
	v_bfe_u32 v103, v103, s16, 16
	v_add3_u32 v8, v8, v100, v101
	v_add3_u32 v8, v8, v102, v103
	v_bfe_u32 v104, v104, s16, 16
	v_bfe_u32 v105, v105, s16, 16
	v_bfe_u32 v106, v106, s16, 16
	v_bfe_u32 v107, v107, s16, 16
	v_add3_u32 v8, v8, v104, v105
	v_add3_u32 v8, v8, v106, v107
	v_bfe_u32 v130, v130, s16, 16
	v_bfe_u32 v131, v131, s16, 16
	v_bfe_u32 v132, v132, s16, 16
	v_bfe_u32 v133, v133, s16, 16
	v_add3_u32 v8, v8, v130, v131
	v_add3_u32 v8, v8, v132, v133
	v_bfe_u32 v190, v190, s16, 16
	v_bfe_u32 v191, v191, s16, 16
	v_bfe_u32 v192, v192, s16, 16
	v_bfe_u32 v193, v193, s16, 16
	v_add3_u32 v8, v8, v190, v191
	v_add3_u32 v8, v8, v192, v193
	v_bfe_u32 v194, v194, s16, 16
	v_bfe_u32 v195, v195, s16, 16
	v_bfe_u32 v196, v196, s16, 16
	v_bfe_u32 v197, v197, s16, 16
	v_add3_u32 v8, v8, v194, v195
	v_add3_u32 v8, v8, v196, v197
	v_bfe_u32 v198, v198, s16, 16
	v_bfe_u32 v199, v199, s16, 16
	v_bfe_u32 v200, v200, s16, 16
	v_bfe_u32 v201, v201, s16, 16
	v_add3_u32 v8, v8, v198, v199
	v_add3_u32 v8, v8, v200, v201
	v_bfe_u32 v230, v230, s16, 16
	v_bfe_u32 v231, v231, s16, 16
	v_bfe_u32 v232, v232, s16, 16
	v_bfe_u32 v233, v233, s16, 16
	v_add3_u32 v8, v8, v230, v231
	v_add3_u32 v8, v8, v232, v233
	v_add_u32_e32 v10, 8, v9
	v_and_b32_e32 v10, 15, v10
	v_lshl_or_b32 v10, v10, 4, v7
	ds_read_b128 v[96:99], v10
	v_add_u32_e32 v10, 9, v9
	v_and_b32_e32 v10, 15, v10
	v_lshl_or_b32 v10, v10, 4, v7
	ds_read_b128 v[100:103], v10
	v_add_u32_e32 v10, 10, v9
	v_and_b32_e32 v10, 15, v10
	v_lshl_or_b32 v10, v10, 4, v7
	ds_read_b128 v[104:107], v10
	v_add_u32_e32 v10, 11, v9
	v_and_b32_e32 v10, 15, v10
	v_lshl_or_b32 v10, v10, 4, v7
	ds_read_b128 v[130:133], v10
	v_add_u32_e32 v10, 12, v9
	v_and_b32_e32 v10, 15, v10
	v_lshl_or_b32 v10, v10, 4, v7
	ds_read_b128 v[190:193], v10
	v_add_u32_e32 v10, 13, v9
	v_and_b32_e32 v10, 15, v10
	v_lshl_or_b32 v10, v10, 4, v7
	ds_read_b128 v[194:197], v10
	v_add_u32_e32 v10, 14, v9
	v_and_b32_e32 v10, 15, v10
	v_lshl_or_b32 v10, v10, 4, v7
	ds_read_b128 v[198:201], v10
	v_add_u32_e32 v10, 15, v9
	v_and_b32_e32 v10, 15, v10
	v_lshl_or_b32 v10, v10, 4, v7
	ds_read_b128 v[230:233], v10
	s_waitcnt lgkmcnt(0)
	v_bfe_u32 v96, v96, s16, 16
	v_bfe_u32 v97, v97, s16, 16
	v_bfe_u32 v98, v98, s16, 16
	v_bfe_u32 v99, v99, s16, 16
	v_add3_u32 v8, v8, v96, v97
	v_add3_u32 v8, v8, v98, v99
	v_bfe_u32 v100, v100, s16, 16
	v_bfe_u32 v101, v101, s16, 16
	v_bfe_u32 v102, v102, s16, 16
	v_bfe_u32 v103, v103, s16, 16
	v_add3_u32 v8, v8, v100, v101
	v_add3_u32 v8, v8, v102, v103
	v_bfe_u32 v104, v104, s16, 16
	v_bfe_u32 v105, v105, s16, 16
	v_bfe_u32 v106, v106, s16, 16
	v_bfe_u32 v107, v107, s16, 16
	v_add3_u32 v8, v8, v104, v105
	v_add3_u32 v8, v8, v106, v107
	v_bfe_u32 v130, v130, s16, 16
	v_bfe_u32 v131, v131, s16, 16
	v_bfe_u32 v132, v132, s16, 16
	v_bfe_u32 v133, v133, s16, 16
	v_add3_u32 v8, v8, v130, v131
	v_add3_u32 v8, v8, v132, v133
	v_bfe_u32 v190, v190, s16, 16
	v_bfe_u32 v191, v191, s16, 16
	v_bfe_u32 v192, v192, s16, 16
	v_bfe_u32 v193, v193, s16, 16
	v_add3_u32 v8, v8, v190, v191
	v_add3_u32 v8, v8, v192, v193
	v_bfe_u32 v194, v194, s16, 16
	v_bfe_u32 v195, v195, s16, 16
	v_bfe_u32 v196, v196, s16, 16
	v_bfe_u32 v197, v197, s16, 16
	v_add3_u32 v8, v8, v194, v195
	v_add3_u32 v8, v8, v196, v197
	v_bfe_u32 v198, v198, s16, 16
	v_bfe_u32 v199, v199, s16, 16
	v_bfe_u32 v200, v200, s16, 16
	v_bfe_u32 v201, v201, s16, 16
	v_add3_u32 v8, v8, v198, v199
	v_add3_u32 v8, v8, v200, v201
	v_bfe_u32 v230, v230, s16, 16
	v_bfe_u32 v231, v231, s16, 16
	v_bfe_u32 v232, v232, s16, 16
	v_bfe_u32 v233, v233, s16, 16
	v_add3_u32 v8, v8, v230, v231
	v_add3_u32 v8, v8, v232, v233
	v_addc_co_u32_e32 v7, vcc, 0, v213, vcc
	v_lshlrev_b32_e32 v7, 2, v7
	v_mov_b32_e32 v1, v8
	ds_bpermute_b32 v8, v7, v1
	v_cmp_gt_u32_e32 vcc, 62, v11
	s_waitcnt lgkmcnt(0)
	v_cndmask_b32_e64 v8, v8, 0, s[0:1]
	v_add_u32_e32 v9, v8, v1
	v_cndmask_b32_e64 v8, 0, 2, vcc
	v_add_lshl_u32 v8, v8, v213, 2
	ds_bpermute_b32 v10, v8, v9
	v_cmp_gt_u32_e32 vcc, 60, v11
	s_waitcnt lgkmcnt(0)
	v_cndmask_b32_e64 v10, 0, v10, s[44:45]
	v_add_u32_e32 v10, v10, v9
	v_cndmask_b32_e64 v9, 0, 4, vcc
	v_add_lshl_u32 v9, v9, v213, 2
	ds_bpermute_b32 v12, v9, v10
	v_cmp_gt_u32_e32 vcc, 56, v11
	s_waitcnt lgkmcnt(0)
	v_cndmask_b32_e64 v12, 0, v12, s[46:47]
	v_add_u32_e32 v12, v12, v10
	v_cndmask_b32_e64 v10, 0, 8, vcc
	v_add_lshl_u32 v10, v10, v213, 2
	ds_bpermute_b32 v13, v10, v12
	v_cmp_gt_u32_e32 vcc, 48, v11
	s_waitcnt lgkmcnt(0)
	v_cndmask_b32_e64 v13, 0, v13, s[48:49]
	v_cndmask_b32_e64 v11, 0, 16, vcc
	v_add_u32_e32 v12, v13, v12
	v_add_lshl_u32 v11, v11, v213, 2
	ds_bpermute_b32 v13, v11, v12
	s_waitcnt lgkmcnt(0)
	v_cndmask_b32_e64 v13, 0, v13, s[50:51]
	v_add_u32_e32 v13, v13, v12
	v_lshl_or_b32 v12, v213, 2, v227
	ds_bpermute_b32 v14, v12, v13
	s_waitcnt lgkmcnt(0)
	v_cndmask_b32_e64 v14, 0, v14, s[52:53]
	v_add_u32_e32 v14, v14, v13
	v_sub_u32_e32 v13, v14, v1
	v_cmp_lt_u32_e32 vcc, v13, v4
	v_cmp_le_u32_e64 s[56:57], v4, v14
	s_and_b64 vcc, s[56:57], vcc
	v_cndmask_b32_e64 v1, 0, 1, vcc
	v_cmp_ne_u32_e64 s[56:57], 0, v1
	s_cbranch_vccz .LBB0_591
; template <int PASS>
; DI void sel_pass(SelSmem* S, const uint32_t (&sk)[32][2], int ntiles, uint32_t (&pf)[2]) {
;     ...
;     if (cm != 0ull) {
;       const int L = __builtin_ctzll(cm);
;       const uint32_t cumbase = (uint32_t)__shfl((int)sfx, L);
;       const uint32_t cnt = (lane < PER) ? ((S->hist[pair][L * PER + lane] >> sh) & 0xffffu) : 0u;
;       uint32_t inc2 = cnt;
; #pragma unroll
;       for (int off = 1; off < PER; off <<= 1) {
;         uint32_t v = __shfl_down(inc2, off);
;         if (lane + off < 64) inc2 += v;
;       }
;       const uint32_t cum = cumbase + (inc2 - cnt);
;       if (lane < PER && cum < need && need <= cum + cnt) {
;         const uint32_t bin = (uint32_t)(L * PER + lane);
;         const uint32_t nn = need - cum;
;         if (PASS == 0) S->pfx[wave] = bin;
;         else if (PASS == 1 || PASS == 2) S->pfx[wave] = (prevp << 10) | bin;
;         else S->dcut[wave] = bin;
;         if (PASS == 2 && cnt != nn) atomicOr(&S->flag, 1u);
;         if (PASS == 1 && cnt != nn) atomicOr(&S->flag, 2u);
;         S->need[wave] = nn;
;       }
	s_ff1_i32_b64 s19, s[56:57]
	v_lshl_or_b32 v1, s19, 6, v5
	v_lshl_add_u32 v5, v1, 2, s18
	ds_read_b32 v5, v5
	s_and_b32 s16, s16, 16
	v_and_or_b32 v16, v213, 64, s19
	v_lshlrev_b32_e32 v16, 2, v16
	ds_bpermute_b32 v13, v16, v13
	s_waitcnt lgkmcnt(1)
	v_lshrrev_b32_e32 v5, s16, v5
	v_and_b32_e32 v5, 0xffff, v5
	ds_bpermute_b32 v14, v7, v5
	s_waitcnt lgkmcnt(0)
	v_cndmask_b32_e64 v14, v14, 0, s[0:1]
	v_add_u32_e32 v14, v5, v14
	ds_bpermute_b32 v15, v8, v14
	s_waitcnt lgkmcnt(0)
	v_cndmask_b32_e64 v15, 0, v15, s[44:45]
	v_add_u32_e32 v14, v14, v15
	ds_bpermute_b32 v15, v9, v14
	s_waitcnt lgkmcnt(0)
	v_cndmask_b32_e64 v15, 0, v15, s[46:47]
	v_add_u32_e32 v14, v14, v15
	ds_bpermute_b32 v15, v10, v14
	s_waitcnt lgkmcnt(0)
	v_cndmask_b32_e64 v15, 0, v15, s[48:49]
	v_add_u32_e32 v14, v14, v15
	ds_bpermute_b32 v15, v11, v14
	s_waitcnt lgkmcnt(0)
	v_cndmask_b32_e64 v15, 0, v15, s[50:51]
	v_add_u32_e32 v14, v14, v15
	ds_bpermute_b32 v15, v12, v14
	s_waitcnt lgkmcnt(0)
	v_cndmask_b32_e64 v15, 0, v15, s[52:53]
	v_add_u32_e32 v14, v14, v15
	v_sub_u32_e32 v5, v14, v5
	v_add_u32_e32 v14, v14, v13
	v_add_u32_e32 v5, v5, v13
	v_cmp_gt_u32_e32 vcc, v4, v5
	v_cmp_le_u32_e64 s[0:1], v4, v14
	s_and_b64 s[18:19], s[0:1], vcc
	s_and_saveexec_b64 s[0:1], s[18:19]
	v_sub_u32_e32 v4, v4, v5
	v_mov_b32_e32 v5, s15
	v_add_u32_e32 v5, 0x8000, v5
	ds_write2_b32 v5, v1, v4 offset1:4
	s_or_b64 exec, exec, s[0:1]
